# gate/up GEMM epilogue copies, half a row group (6KB) per wave per unit, 5 rounds; a fifth of the plain-copy units moved
# speedup vs baseline: 1.0234x; 1.0234x over previous
.LBB0_1208:
	s_add_i32 s95, s95, 1
	s_mul_i32 s8, s95, s40
	s_mov_b32 s82, s40
	s_cmpk_gt_i32 s8, 0x3cff
	s_cbranch_scc1 .LBB0_1379
.LBB0_1209:
	v_readlane_b32 s10, v240, 0
	s_add_i32 s12, s8, s10
	s_lshl_b32 s8, s95, 8
	s_add_i32 s8, s8, s15
	s_ashr_i32 s9, s8, 7
	v_readlane_b32 s11, v240, 1
	s_mul_hi_i32 s10, s9, 0x55555556
	s_lshr_b32 s11, s10, 31
	s_add_i32 s10, s10, s11
	s_mul_i32 s11, s14, 3
	s_add_i32 s11, s10, s11
	s_mul_i32 s10, s10, 3
	s_mul_i32 s11, s11, 3
	s_sub_i32 s10, s9, s10
	s_add_i32 s11, s11, s10
	s_mul_hi_i32 s10, s8, 0x30c30c31
	s_lshr_b32 s16, s10, 31
	s_ashr_i32 s10, s10, 4
	s_add_i32 s10, s10, s16
	s_lshl_b32 s16, s10, 3
	s_or_b32 s16, s16, s14
	s_mulk_i32 s10, 0x54
	s_mulk_i32 s16, 0x54
	s_sub_i32 s10, s8, s10
	s_add_i32 s13, s12, 0x2a00
	s_add_i32 s96, s12, 0xffffdb00
	s_add_i32 s16, s16, s10
	s_cmp_lt_u32 s9, 12
	s_cselect_b32 s10, s19, s2
	s_add_i32 s10, s10, s9
	s_cmp_lt_i32 s9, 9
	s_cselect_b32 s9, s11, s10
	s_lshl_b32 s9, s9, 7
	s_add_i32 s17, s9, s35
	s_cmpk_lt_i32 s8, 0x540
	s_cselect_b32 s10, s16, -1
	s_and_b64 s[8:9], s[58:59], exec
	s_cselect_b32 s16, s12, s10
	s_cmpk_gt_i32 s12, 0x29ff
	s_cselect_b64 s[8:9], -1, 0
	s_and_b64 s[10:11], s[8:9], exec
	s_cselect_b32 s97, -1, s16
	s_or_b64 s[8:9], s[8:9], s[58:59]
	s_cmpk_lt_u32 s96, 0x1800
	s_cselect_b64 s[10:11], -1, 0
	s_and_b64 s[74:75], s[8:9], s[10:11]
	s_and_b64 s[8:9], s[58:59], exec
	s_cselect_b32 s8, s13, s17
	s_cmpk_lt_i32 s12, 0x3800
	s_mov_b32 s40, s82
	s_cselect_b32 s52, s8, -1
	s_mov_b64 s[76:77], -1
	s_mov_b32 s10, s57
	s_branch .LBB0_1212

.LBB0_1649:
	s_or_b64 exec, exec, s[6:7]
	s_add_u32 s8, s30, 0xfc00000
	s_addc_u32 s9, s31, 0
	v_mov_b32_e32 v10, v164
	s_waitcnt lgkmcnt(0)
	s_barrier
	s_cmpk_gt_i32 s69, 0x5d7
	v_readfirstlane_b32 s7, v10
	s_cbranch_scc1 .LBB0_1665
	v_writelane_b32 v247, s78, 0
	v_writelane_b32 v247, s79, 1
	v_writelane_b32 v247, s4, 2
	v_writelane_b32 v247, s5, 3
	s_lshr_b32 s32, s69, 7
	s_lshl_b32 s32, s32, 3
	s_load_dwordx2 s[96:97], s[0:1], s32 offset:0x20
	s_load_dwordx2 s[76:77], s[0:1], 0xa0
	s_and_b32 s100, s69, 0x7f
	s_mul_i32 s100, s100, 0x300000
	s_mov_b32 s101, 0x1ee80000
	s_cmp_lt_u32 s69, 0x80
	s_cselect_b32 s101, 0x6e80000, s101
	v_and_b32_e32 v246, 63, v164
	v_lshlrev_b32_e32 v246, 4, v246
	s_waitcnt lgkmcnt(0)
	s_add_u32 s96, s96, s100
	s_addc_u32 s97, s97, 0
	s_add_u32 s96, s96, 0x3000
	s_addc_u32 s97, s97, 0
	s_and_b32 s97, s97, 0xffff
	s_mov_b32 s98, 0x300000
	s_mov_b32 s99, 0x20000
	s_add_u32 s76, s76, s101
	s_addc_u32 s77, s77, 0
	s_add_u32 s76, s76, s100
	s_addc_u32 s77, s77, 0
	s_and_b32 s77, s77, 0xffff
	s_mov_b32 s78, 0x300000
	s_mov_b32 s79, 0x20000
	s_lshr_b32 s32, s7, 6
	s_mul_i32 s101, s32, 0x0
	s_add_u32 s100, s101, 0x0
	s_lshr_b32 s5, s32, 1
	s_mul_i32 s5, s5, 0x6000
	s_and_b32 s4, s32, 1
	s_mul_i32 s4, s4, 0x1800
	s_add_u32 s5, s5, s4
	s_add_u32 s5, s5, 0x0
	s_mov_b32 s32, 0
	s_mov_b32 s4, 0
	v_add_u32_e32 v238, 0x1000, v246
	v_add_u32_e32 v239, 0x2000, v246
	s_mov_b32 s100, 0x70000000
	s_mov_b32 s101, 0x70000000
	v_lshlrev_b32_e32 v0, 4, v10
	v_add_u32_e32 v1, 0x2000, v0
	v_ashrrev_i32_e32 v2, 31, v1
	v_lshrrev_b32_e32 v2, 22, v2
	v_add_u32_e32 v2, v1, v2
	v_ashrrev_i32_e32 v8, 10, v2
	v_mul_i32_i24_e32 v2, 0x400, v8
	v_sub_u32_e32 v1, v1, v2
	v_lshrrev_b32_e32 v2, 4, v1
	v_bitop3_b32 v1, v2, v1, 32 bitop3:0x6c
	v_ashrrev_i32_e32 v2, 31, v1
	v_lshrrev_b32_e32 v2, 26, v2
	v_add_u32_e32 v2, v1, v2
	v_lshlrev_b32_e32 v3, 3, v8
	v_ashrrev_i32_e32 v9, 6, v2
	v_and_b32_e32 v3, -16, v3
	v_add_u32_e32 v3, v9, v3
	v_and_b32_e32 v4, 3, v9
	s_mov_b32 s6, 0x1fffe0
	v_lshrrev_b32_e32 v5, 2, v3
	v_lshlrev_b32_e32 v6, 1, v3
	v_and_b32_e32 v2, 0xc0, v2
	v_and_or_b32 v4, v3, s6, v4
	v_and_b32_e32 v5, 4, v5
	v_and_b32_e32 v6, 24, v6
	v_sub_u32_e32 v1, v1, v2
	v_mov_b32_e32 v2, 1
	v_or3_b32 v4, v4, v5, v6
	v_lshlrev_b32_e32 v5, 5, v8
	v_ashrrev_i16_sdwa v1, v2, sext(v1) dst_sel:DWORD dst_unused:UNUSED_PAD src0_sel:DWORD src1_sel:BYTE_0
	v_and_b32_e32 v5, 32, v5
	v_bfe_i32 v11, v1, 0, 16
	v_add_lshl_u32 v1, v5, v11, 1
	v_lshl_add_u32 v130, v4, 11, v1
	v_lshl_add_u32 v132, v3, 11, v1
	v_bfe_i32 v1, v10, 27, 1
	v_lshrrev_b32_e32 v1, 22, v1
	v_add_u32_e32 v1, v0, v1
	v_and_b32_e32 v1, 0xfffffc00, v1
	v_sub_u32_e32 v0, v0, v1
	v_lshrrev_b32_e32 v1, 4, v0
	v_ashrrev_i32_e32 v3, 31, v10
	v_bitop3_b32 v0, v1, v0, 32 bitop3:0x6c
	v_lshrrev_b32_e32 v3, 26, v3
	v_ashrrev_i32_e32 v1, 31, v0
	v_add_u32_e32 v3, v10, v3
	v_lshrrev_b32_e32 v1, 26, v1
	v_ashrrev_i32_e32 v13, 6, v3
	v_add_u32_e32 v1, v0, v1
	v_lshlrev_b32_e32 v3, 3, v13
	v_ashrrev_i32_e32 v12, 6, v1
	v_and_b32_e32 v3, -16, v3
	v_add_u32_e32 v3, v12, v3
	v_and_b32_e32 v4, 3, v12
	s_ashr_i32 s14, s69, 31
	v_and_or_b32 v4, v3, s6, v4
	s_lshr_b32 s6, s14, 29
	s_add_i32 s6, s69, s6
	s_ashr_i32 s2, s7, 6
	s_ashr_i32 s11, s6, 3
	s_and_b32 s6, s6, -8
	s_ashr_i32 s10, s7, 8
	s_lshl_b32 s3, s2, 10
	s_sub_i32 s6, s69, s6
	s_cmp_lt_i32 s6, 0
	s_movk_i32 s15, 0xbc
	s_cselect_b32 s18, s15, 0xbb
	s_mul_i32 s6, s6, s18
	s_add_i32 s6, s6, s11
	s_mul_hi_i32 s11, s6, 0x2e8ba2e9
	s_lshr_b32 s18, s11, 31
	s_ashr_i32 s11, s11, 5
	v_lshrrev_b32_e32 v5, 2, v3
	v_lshlrev_b32_e32 v6, 1, v3
	v_and_b32_e32 v1, 0xc0, v1
	s_add_i32 s11, s11, s18
	v_and_b32_e32 v5, 4, v5
	v_and_b32_e32 v6, 24, v6
	v_sub_u32_e32 v0, v0, v1
	s_lshl_b32 s22, s11, 3
	v_or3_b32 v4, v4, v5, v6
	v_lshlrev_b32_e32 v5, 5, v13
	v_ashrrev_i16_sdwa v0, v2, sext(v0) dst_sel:DWORD dst_unused:UNUSED_PAD src0_sel:DWORD src1_sel:BYTE_0
	s_sub_i32 s18, 0x44, s22
	s_mulk_i32 s11, 0xb0
	v_and_b32_e32 v5, 32, v5
	v_bfe_i32 v14, v0, 0, 16
	s_min_u32 s23, s18, 8
	s_sub_i32 s11, s6, s11
	v_add_lshl_u32 v0, v5, v14, 1
	s_sext_i32_i16 s6, s11
	v_cvt_f32_ubyte0_e32 v2, s23
	v_lshl_add_u32 v134, v4, 11, v0
	v_cvt_f32_i32_e32 v1, s6
	v_rcp_iflag_f32_e32 v4, v2
	v_lshl_add_u32 v136, v3, 11, v0
	s_ashr_i32 s6, s6, 30
	s_or_b32 s6, s6, 1
	v_mul_f32_e32 v0, v1, v4
	v_trunc_f32_e32 v0, v0
	v_fma_f32 v1, -v0, v2, v1
	v_cvt_i32_f32_e32 v0, v0
	v_cmp_ge_f32_e64 s[18:19], |v1|, v2
	s_and_b64 s[18:19], s[18:19], exec
	s_cselect_b32 s6, s6, 0
	v_readfirstlane_b32 s18, v0
	s_add_i32 s6, s18, s6
	s_mul_i32 s18, s6, s23
	s_sub_i32 s11, s11, s18
	s_sext_i32_i16 s11, s11
	s_add_i32 s56, s22, s11
	s_ashr_i32 s57, s56, 31
	s_bfe_i64 s[18:19], s[6:7], 0x100000
	s_lshl_b64 s[22:23], s[56:57], 19
	s_lshl_b64 s[18:19], s[18:19], 19
	s_add_u32 s60, s92, s18
	s_addc_u32 s61, s93, s19
	s_add_i32 s18, s3, 0
	s_add_i32 m0, s18, 0x10000
	v_mov_b32_e32 v139, 0
	global_load_lds_dwordx4 v134, s[60:61]
	s_add_i32 m0, s18, 0x12000
	s_add_u32 s24, s60, 0x40000
	global_load_lds_dwordx4 v130, s[60:61]
	s_addc_u32 s25, s61, 0
	s_add_i32 m0, s18, 0x14000
	v_mov_b32_e32 v135, v139
	global_load_lds_dwordx4 v134, s[24:25]
	s_add_i32 m0, s18, 0x16000
	s_add_u32 s58, s94, s22
	s_addc_u32 s59, s95, s23
	s_add_i32 s19, s18, 0x2000
	global_load_lds_dwordx4 v130, s[24:25]
	s_mov_b32 m0, s18
	s_add_u32 s22, s58, 0x40000
	global_load_lds_dwordx4 v136, s[58:59]
	s_mov_b32 m0, s19
	s_addc_u32 s23, s59, 0
	s_add_i32 s35, s18, 0x4000
	global_load_lds_dwordx4 v132, s[58:59]
	s_mov_b32 m0, s35
	s_add_i32 s43, s18, 0x6000
	global_load_lds_dwordx4 v136, s[22:23]
	s_mov_b32 m0, s43
	v_mov_b32_e32 v131, v139
	global_load_lds_dwordx4 v132, s[22:23]
	v_mov_b32_e32 v137, v139
	v_mov_b32_e32 v133, v139
	s_cmp_eq_u32 s10, 1
	s_mov_b32 s11, 0
	v_lshl_add_u64 v[6:7], s[60:61], 0, v[134:135]
	v_lshl_add_u64 v[4:5], s[60:61], 0, v[130:131]
	v_lshl_add_u64 v[0:1], s[58:59], 0, v[136:137]
	s_cselect_b64 s[22:23], -1, 0
	s_cmp_lg_u32 s10, 1
	v_lshl_add_u64 v[2:3], s[58:59], 0, v[132:133]
	s_cbranch_scc1 .LBB0_1652
	s_barrier

.LBB0_1661:
	s_add_u32 vcc_lo, s5, 0x1000
	buffer_load_dwordx4 v[166:169], v246, s[96:99], s5 offen nt
	buffer_load_dwordx4 v[170:173], v246, s[96:99], s5 offen offset:1024 nt
	buffer_load_dwordx4 v[174:177], v246, s[96:99], s5 offen offset:2048 nt
	buffer_load_dwordx4 v[178:181], v246, s[96:99], s5 offen offset:3072 nt
	buffer_load_dwordx4 v[182:185], v246, s[96:99], vcc_lo offen nt
	buffer_load_dwordx4 v[186:189], v246, s[96:99], vcc_lo offen offset:1024 nt
	v_mul_f32_e32 v153, 0xbfb8aa3b, v124
	v_exp_f32_e32 v153, v153
	v_mul_f32_e32 v154, 0xbfb8aa3b, v125
	v_exp_f32_e32 v155, v154
	s_lshl_b32 s48, s2, 7
	v_add_f32_e32 v153, 1.0, v153
	v_rcp_f32_e32 v154, v153
	v_add_f32_e32 v153, 1.0, v155
	v_mul_f32_e32 v155, 0xbfb8aa3b, v126
	v_exp_f32_e32 v156, v155
	v_mul_f32_e32 v155, 0xbfb8aa3b, v127
	v_exp_f32_e32 v157, v155
	v_rcp_f32_e32 v155, v153
	v_add_f32_e32 v153, 1.0, v156
	v_rcp_f32_e32 v156, v153
	v_add_f32_e32 v153, 1.0, v157
	v_rcp_f32_e32 v157, v153
	v_pk_mul_f32 v[124:125], v[124:125], v[154:155]
	v_mul_f32_e32 v153, 0xbfb8aa3b, v118
	v_pk_mul_f32 v[120:121], v[120:121], v[124:125]
	v_pk_mul_f32 v[124:125], v[126:127], v[156:157]
	v_mul_f32_e32 v126, 0xbfb8aa3b, v116
	v_mul_f32_e32 v127, 0xbfb8aa3b, v117
	v_exp_f32_e32 v126, v126
	v_exp_f32_e32 v127, v127
	v_exp_f32_e32 v153, v153
	v_mul_f32_e32 v154, 0xbfb8aa3b, v119
	v_exp_f32_e32 v155, v154
	v_add_f32_e32 v126, 1.0, v126
	v_add_f32_e32 v127, 1.0, v127
	v_add_f32_e32 v153, 1.0, v153
	v_rcp_f32_e32 v126, v126
	v_rcp_f32_e32 v127, v127
	v_rcp_f32_e32 v154, v153
	v_add_f32_e32 v153, 1.0, v155
	v_rcp_f32_e32 v155, v153
	v_pk_mul_f32 v[116:117], v[116:117], v[126:127]
	v_lshl_add_u32 v152, s56, 8, v129
	v_pk_mul_f32 v[112:113], v[112:113], v[116:117]
	v_pk_mul_f32 v[116:117], v[118:119], v[154:155]
	s_ashr_i32 s49, s48, 31
	v_pk_mul_f32 v[114:115], v[114:115], v[116:117]
	v_pk_mul_f32 v[122:123], v[122:123], v[124:125]
	v_cvt_pk_bf16_f32 v124, v120, v121
	v_mov_b64_e32 v[120:121], s[8:9]
	v_cvt_pk_bf16_f32 v112, v112, v113
	v_cvt_pk_bf16_f32 v113, v114, v115
	v_mul_f32_e32 v114, 0xbfb8aa3b, v108
	v_mul_f32_e32 v115, 0xbfb8aa3b, v109
	v_cvt_pk_bf16_f32 v125, v122, v123
	v_mad_i64_i32 v[122:123], s[50:51], v152, s66, v[120:121]
	s_lshl_b64 s[56:57], s[48:49], 1
	v_exp_f32_e32 v114, v114
	v_exp_f32_e32 v115, v115
	v_lshl_add_u64 v[122:123], v[122:123], 0, s[56:57]
	v_lshl_add_u64 v[122:123], v[122:123], 0, s[10:11]
	v_lshl_add_u64 v[122:123], v[122:123], 0, v[138:139]
	global_store_dwordx2 v[122:123], v[112:113], off offset:128
	v_add_f32_e32 v112, 1.0, v114
	v_add_f32_e32 v113, 1.0, v115
	v_mul_f32_e32 v114, 0xbfb8aa3b, v110
	v_mul_f32_e32 v115, 0xbfb8aa3b, v111
	v_exp_f32_e32 v114, v114
	v_exp_f32_e32 v115, v115
	v_rcp_f32_e32 v112, v112
	v_rcp_f32_e32 v113, v113
	v_add_f32_e32 v114, 1.0, v114
	v_add_f32_e32 v115, 1.0, v115
	v_rcp_f32_e32 v114, v114
	v_rcp_f32_e32 v115, v115
	v_pk_mul_f32 v[108:109], v[108:109], v[112:113]
	v_or_b32_e32 v116, 16, v152
	v_pk_mul_f32 v[104:105], v[104:105], v[108:109]
	v_pk_mul_f32 v[108:109], v[110:111], v[114:115]
	v_mul_f32_e32 v110, 0xbfb8aa3b, v102
	v_pk_mul_f32 v[106:107], v[106:107], v[108:109]
	v_mul_f32_e32 v108, 0xbfb8aa3b, v100
	v_mul_f32_e32 v109, 0xbfb8aa3b, v101
	v_exp_f32_e32 v108, v108
	v_exp_f32_e32 v109, v109
	v_mul_f32_e32 v111, 0xbfb8aa3b, v103
	v_exp_f32_e32 v110, v110
	v_exp_f32_e32 v111, v111
	v_add_f32_e32 v108, 1.0, v108
	v_add_f32_e32 v109, 1.0, v109
	v_rcp_f32_e32 v108, v108
	v_rcp_f32_e32 v109, v109
	v_add_f32_e32 v110, 1.0, v110
	v_add_f32_e32 v111, 1.0, v111
	v_rcp_f32_e32 v110, v110
	v_rcp_f32_e32 v111, v111
	v_pk_mul_f32 v[100:101], v[100:101], v[108:109]
	v_cvt_pk_bf16_f32 v104, v104, v105
	v_pk_mul_f32 v[96:97], v[96:97], v[100:101]
	v_pk_mul_f32 v[100:101], v[102:103], v[110:111]
	v_cvt_pk_bf16_f32 v96, v96, v97
	v_pk_mul_f32 v[98:99], v[98:99], v[100:101]
	v_cvt_pk_bf16_f32 v105, v106, v107
	v_cvt_pk_bf16_f32 v97, v98, v99
	v_mul_f32_e32 v98, 0xbfb8aa3b, v92
	v_mul_f32_e32 v99, 0xbfb8aa3b, v93
	v_mad_i64_i32 v[106:107], s[48:49], v116, s66, v[120:121]
	v_exp_f32_e32 v98, v98
	v_exp_f32_e32 v99, v99
	v_lshl_add_u64 v[106:107], v[106:107], 0, s[56:57]
	v_lshl_add_u64 v[106:107], v[106:107], 0, s[10:11]
	v_lshl_add_u64 v[106:107], v[106:107], 0, v[138:139]
	global_store_dwordx2 v[106:107], v[96:97], off offset:128
	v_add_f32_e32 v96, 1.0, v98
	v_add_f32_e32 v97, 1.0, v99
	v_mul_f32_e32 v98, 0xbfb8aa3b, v94
	v_mul_f32_e32 v99, 0xbfb8aa3b, v95
	v_exp_f32_e32 v98, v98
	v_exp_f32_e32 v99, v99
	v_rcp_f32_e32 v96, v96
	v_rcp_f32_e32 v97, v97
	v_add_f32_e32 v98, 1.0, v98
	v_add_f32_e32 v99, 1.0, v99
	v_rcp_f32_e32 v98, v98
	v_rcp_f32_e32 v99, v99
	v_pk_mul_f32 v[92:93], v[92:93], v[96:97]
	v_or_b32_e32 v100, 32, v152
	v_pk_mul_f32 v[88:89], v[88:89], v[92:93]
	v_pk_mul_f32 v[92:93], v[94:95], v[98:99]
	v_mul_f32_e32 v94, 0xbfb8aa3b, v86
	v_pk_mul_f32 v[90:91], v[90:91], v[92:93]
	v_mul_f32_e32 v92, 0xbfb8aa3b, v84
	v_mul_f32_e32 v93, 0xbfb8aa3b, v85
	v_exp_f32_e32 v92, v92
	v_exp_f32_e32 v93, v93
	v_mul_f32_e32 v95, 0xbfb8aa3b, v87
	v_exp_f32_e32 v94, v94
	v_exp_f32_e32 v95, v95
	v_add_f32_e32 v92, 1.0, v92
	v_add_f32_e32 v93, 1.0, v93
	v_rcp_f32_e32 v92, v92
	v_rcp_f32_e32 v93, v93
	v_add_f32_e32 v94, 1.0, v94
	v_add_f32_e32 v95, 1.0, v95
	v_rcp_f32_e32 v94, v94
	v_rcp_f32_e32 v95, v95
	v_pk_mul_f32 v[84:85], v[84:85], v[92:93]
	v_cvt_pk_bf16_f32 v88, v88, v89
	v_pk_mul_f32 v[80:81], v[80:81], v[84:85]
	v_pk_mul_f32 v[84:85], v[86:87], v[94:95]
	v_cvt_pk_bf16_f32 v80, v80, v81
	v_pk_mul_f32 v[82:83], v[82:83], v[84:85]
	v_cvt_pk_bf16_f32 v89, v90, v91
	v_cvt_pk_bf16_f32 v81, v82, v83
	v_mul_f32_e32 v82, 0xbfb8aa3b, v76
	v_mul_f32_e32 v83, 0xbfb8aa3b, v77
	v_mad_i64_i32 v[90:91], s[48:49], v100, s66, v[120:121]
	v_exp_f32_e32 v82, v82
	v_exp_f32_e32 v83, v83
	v_lshl_add_u64 v[90:91], v[90:91], 0, s[56:57]
	v_lshl_add_u64 v[90:91], v[90:91], 0, s[10:11]
	v_lshl_add_u64 v[90:91], v[90:91], 0, v[138:139]
	global_store_dwordx2 v[90:91], v[80:81], off offset:128
	v_add_f32_e32 v80, 1.0, v82
	v_add_f32_e32 v81, 1.0, v83
	v_mul_f32_e32 v82, 0xbfb8aa3b, v78
	v_mul_f32_e32 v83, 0xbfb8aa3b, v79
	v_exp_f32_e32 v82, v82
	v_exp_f32_e32 v83, v83
	v_rcp_f32_e32 v80, v80
	v_rcp_f32_e32 v81, v81
	v_add_f32_e32 v82, 1.0, v82
	v_add_f32_e32 v83, 1.0, v83
	v_rcp_f32_e32 v82, v82
	v_rcp_f32_e32 v83, v83
	v_pk_mul_f32 v[76:77], v[76:77], v[80:81]
	v_or_b32_e32 v84, 48, v152
	v_pk_mul_f32 v[72:73], v[72:73], v[76:77]
	v_pk_mul_f32 v[76:77], v[78:79], v[82:83]
	v_mul_f32_e32 v78, 0xbfb8aa3b, v70
	v_pk_mul_f32 v[74:75], v[74:75], v[76:77]
	v_mul_f32_e32 v76, 0xbfb8aa3b, v68
	v_mul_f32_e32 v77, 0xbfb8aa3b, v69
	v_exp_f32_e32 v76, v76
	v_exp_f32_e32 v77, v77
	v_mul_f32_e32 v79, 0xbfb8aa3b, v71
	v_exp_f32_e32 v78, v78
	v_exp_f32_e32 v79, v79
	v_add_f32_e32 v76, 1.0, v76
	v_add_f32_e32 v77, 1.0, v77
	v_rcp_f32_e32 v76, v76
	v_rcp_f32_e32 v77, v77
	v_add_f32_e32 v78, 1.0, v78
	v_add_f32_e32 v79, 1.0, v79
	v_rcp_f32_e32 v78, v78
	v_rcp_f32_e32 v79, v79
	v_pk_mul_f32 v[68:69], v[68:69], v[76:77]
	v_cvt_pk_bf16_f32 v72, v72, v73
	v_pk_mul_f32 v[64:65], v[64:65], v[68:69]
	v_pk_mul_f32 v[68:69], v[70:71], v[78:79]
	v_cvt_pk_bf16_f32 v64, v64, v65
	v_pk_mul_f32 v[66:67], v[66:67], v[68:69]
	v_cvt_pk_bf16_f32 v73, v74, v75
	v_cvt_pk_bf16_f32 v65, v66, v67
	v_mul_f32_e32 v66, 0xbfb8aa3b, v60
	v_mul_f32_e32 v67, 0xbfb8aa3b, v61
	v_mad_i64_i32 v[74:75], s[48:49], v84, s66, v[120:121]
	v_exp_f32_e32 v66, v66
	v_exp_f32_e32 v67, v67
	v_lshl_add_u64 v[74:75], v[74:75], 0, s[56:57]
	v_lshl_add_u64 v[74:75], v[74:75], 0, s[10:11]
	v_lshl_add_u64 v[74:75], v[74:75], 0, v[138:139]
	global_store_dwordx2 v[74:75], v[64:65], off offset:128
	v_add_f32_e32 v64, 1.0, v66
	v_add_f32_e32 v65, 1.0, v67
	v_mul_f32_e32 v66, 0xbfb8aa3b, v62
	v_mul_f32_e32 v67, 0xbfb8aa3b, v63
	v_exp_f32_e32 v66, v66
	v_exp_f32_e32 v67, v67
	v_rcp_f32_e32 v64, v64
	v_rcp_f32_e32 v65, v65
	v_add_f32_e32 v66, 1.0, v66
	v_add_f32_e32 v67, 1.0, v67
	v_rcp_f32_e32 v66, v66
	v_rcp_f32_e32 v67, v67
	v_pk_mul_f32 v[60:61], v[60:61], v[64:65]
	v_add_u32_e32 v68, 0x80, v152
	v_pk_mul_f32 v[56:57], v[56:57], v[60:61]
	v_pk_mul_f32 v[60:61], v[62:63], v[66:67]
	v_mul_f32_e32 v62, 0xbfb8aa3b, v54
	v_pk_mul_f32 v[58:59], v[58:59], v[60:61]
	v_mul_f32_e32 v60, 0xbfb8aa3b, v52
	v_mul_f32_e32 v61, 0xbfb8aa3b, v53
	v_exp_f32_e32 v60, v60
	v_exp_f32_e32 v61, v61
	v_mul_f32_e32 v63, 0xbfb8aa3b, v55
	v_exp_f32_e32 v62, v62
	v_exp_f32_e32 v63, v63
	v_add_f32_e32 v60, 1.0, v60
	v_add_f32_e32 v61, 1.0, v61
	v_rcp_f32_e32 v60, v60
	v_rcp_f32_e32 v61, v61
	v_add_f32_e32 v62, 1.0, v62
	v_add_f32_e32 v63, 1.0, v63
	v_rcp_f32_e32 v62, v62
	v_rcp_f32_e32 v63, v63
	v_pk_mul_f32 v[52:53], v[52:53], v[60:61]
	v_cvt_pk_bf16_f32 v56, v56, v57
	v_pk_mul_f32 v[48:49], v[48:49], v[52:53]
	v_pk_mul_f32 v[52:53], v[54:55], v[62:63]
	v_cvt_pk_bf16_f32 v48, v48, v49
	v_pk_mul_f32 v[50:51], v[50:51], v[52:53]
	v_cvt_pk_bf16_f32 v57, v58, v59
	v_cvt_pk_bf16_f32 v49, v50, v51
	v_mul_f32_e32 v50, 0xbfb8aa3b, v44
	v_mul_f32_e32 v51, 0xbfb8aa3b, v45
	v_mad_i64_i32 v[58:59], s[48:49], v68, s66, v[120:121]
	v_exp_f32_e32 v50, v50
	v_exp_f32_e32 v51, v51
	v_lshl_add_u64 v[58:59], v[58:59], 0, s[56:57]
	v_lshl_add_u64 v[58:59], v[58:59], 0, s[10:11]
	v_lshl_add_u64 v[58:59], v[58:59], 0, v[138:139]
	global_store_dwordx2 v[58:59], v[48:49], off offset:128
	v_add_f32_e32 v48, 1.0, v50
	v_add_f32_e32 v49, 1.0, v51
	v_mul_f32_e32 v50, 0xbfb8aa3b, v46
	v_mul_f32_e32 v51, 0xbfb8aa3b, v47
	v_exp_f32_e32 v50, v50
	v_exp_f32_e32 v51, v51
	v_rcp_f32_e32 v48, v48
	v_rcp_f32_e32 v49, v49
	v_add_f32_e32 v50, 1.0, v50
	v_add_f32_e32 v51, 1.0, v51
	v_rcp_f32_e32 v50, v50
	v_rcp_f32_e32 v51, v51
	v_pk_mul_f32 v[44:45], v[44:45], v[48:49]
	v_add_u32_e32 v52, 0x90, v152
	v_pk_mul_f32 v[40:41], v[40:41], v[44:45]
	v_pk_mul_f32 v[44:45], v[46:47], v[50:51]
	v_mul_f32_e32 v46, 0xbfb8aa3b, v38
	v_pk_mul_f32 v[42:43], v[42:43], v[44:45]
	v_mul_f32_e32 v44, 0xbfb8aa3b, v36
	v_mul_f32_e32 v45, 0xbfb8aa3b, v37
	v_exp_f32_e32 v44, v44
	v_exp_f32_e32 v45, v45
	v_mul_f32_e32 v47, 0xbfb8aa3b, v39
	v_exp_f32_e32 v46, v46
	v_exp_f32_e32 v47, v47
	v_add_f32_e32 v44, 1.0, v44
	v_add_f32_e32 v45, 1.0, v45
	v_rcp_f32_e32 v44, v44
	v_rcp_f32_e32 v45, v45
	v_add_f32_e32 v46, 1.0, v46
	v_add_f32_e32 v47, 1.0, v47
	v_rcp_f32_e32 v46, v46
	v_rcp_f32_e32 v47, v47
	v_pk_mul_f32 v[36:37], v[36:37], v[44:45]
	v_cvt_pk_bf16_f32 v40, v40, v41
	v_pk_mul_f32 v[32:33], v[32:33], v[36:37]
	v_pk_mul_f32 v[36:37], v[38:39], v[46:47]
	v_cvt_pk_bf16_f32 v32, v32, v33
	v_pk_mul_f32 v[34:35], v[34:35], v[36:37]
	v_cvt_pk_bf16_f32 v41, v42, v43
	v_cvt_pk_bf16_f32 v33, v34, v35
	v_mul_f32_e32 v34, 0xbfb8aa3b, v28
	v_mul_f32_e32 v35, 0xbfb8aa3b, v29
	v_mad_i64_i32 v[42:43], s[48:49], v52, s66, v[120:121]
	v_exp_f32_e32 v34, v34
	v_exp_f32_e32 v35, v35
	v_lshl_add_u64 v[42:43], v[42:43], 0, s[56:57]
	v_lshl_add_u64 v[42:43], v[42:43], 0, s[10:11]
	v_lshl_add_u64 v[42:43], v[42:43], 0, v[138:139]
	global_store_dwordx2 v[42:43], v[32:33], off offset:128
	v_add_f32_e32 v32, 1.0, v34
	v_add_f32_e32 v33, 1.0, v35
	v_mul_f32_e32 v34, 0xbfb8aa3b, v30
	v_mul_f32_e32 v35, 0xbfb8aa3b, v31
	v_exp_f32_e32 v34, v34
	v_exp_f32_e32 v35, v35
	v_rcp_f32_e32 v32, v32
	v_rcp_f32_e32 v33, v33
	v_add_f32_e32 v34, 1.0, v34
	v_add_f32_e32 v35, 1.0, v35
	v_rcp_f32_e32 v34, v34
	v_rcp_f32_e32 v35, v35
	v_pk_mul_f32 v[28:29], v[28:29], v[32:33]
	v_add_u32_e32 v36, 0xa0, v152
	v_pk_mul_f32 v[24:25], v[24:25], v[28:29]
	v_pk_mul_f32 v[28:29], v[30:31], v[34:35]
	v_mul_f32_e32 v30, 0xbfb8aa3b, v22
	v_pk_mul_f32 v[26:27], v[26:27], v[28:29]
	v_mul_f32_e32 v28, 0xbfb8aa3b, v20
	v_mul_f32_e32 v29, 0xbfb8aa3b, v21
	v_exp_f32_e32 v28, v28
	v_exp_f32_e32 v29, v29
	v_mul_f32_e32 v31, 0xbfb8aa3b, v23
	v_exp_f32_e32 v30, v30
	v_exp_f32_e32 v31, v31
	v_add_f32_e32 v28, 1.0, v28
	v_add_f32_e32 v29, 1.0, v29
	v_rcp_f32_e32 v28, v28
	v_rcp_f32_e32 v29, v29
	v_add_f32_e32 v30, 1.0, v30
	v_add_f32_e32 v31, 1.0, v31
	v_rcp_f32_e32 v30, v30
	v_rcp_f32_e32 v31, v31
	v_pk_mul_f32 v[20:21], v[20:21], v[28:29]
	v_cvt_pk_bf16_f32 v24, v24, v25
	v_pk_mul_f32 v[16:17], v[16:17], v[20:21]
	v_pk_mul_f32 v[20:21], v[22:23], v[30:31]
	v_cvt_pk_bf16_f32 v16, v16, v17
	v_pk_mul_f32 v[18:19], v[18:19], v[20:21]
	v_cvt_pk_bf16_f32 v25, v26, v27
	v_cvt_pk_bf16_f32 v17, v18, v19
	v_mul_f32_e32 v18, 0xbfb8aa3b, v12
	v_mul_f32_e32 v19, 0xbfb8aa3b, v13
	v_mad_i64_i32 v[26:27], s[48:49], v36, s66, v[120:121]
	v_exp_f32_e32 v18, v18
	v_exp_f32_e32 v19, v19
	v_lshl_add_u64 v[26:27], v[26:27], 0, s[56:57]
	v_lshl_add_u64 v[26:27], v[26:27], 0, s[10:11]
	v_lshl_add_u64 v[26:27], v[26:27], 0, v[138:139]
	global_store_dwordx2 v[26:27], v[16:17], off offset:128
	v_add_f32_e32 v16, 1.0, v18
	v_add_f32_e32 v17, 1.0, v19
	v_mul_f32_e32 v18, 0xbfb8aa3b, v14
	v_mul_f32_e32 v19, 0xbfb8aa3b, v15
	v_exp_f32_e32 v18, v18
	v_exp_f32_e32 v19, v19
	v_rcp_f32_e32 v16, v16
	v_rcp_f32_e32 v17, v17
	v_add_f32_e32 v18, 1.0, v18
	v_add_f32_e32 v19, 1.0, v19
	v_rcp_f32_e32 v18, v18
	v_rcp_f32_e32 v19, v19
	v_pk_mul_f32 v[12:13], v[12:13], v[16:17]
	v_add_u32_e32 v20, 0xb0, v152
	v_pk_mul_f32 v[8:9], v[8:9], v[12:13]
	v_pk_mul_f32 v[12:13], v[14:15], v[18:19]
	v_mul_f32_e32 v14, 0xbfb8aa3b, v6
	v_pk_mul_f32 v[10:11], v[10:11], v[12:13]
	v_mul_f32_e32 v12, 0xbfb8aa3b, v4
	v_mul_f32_e32 v13, 0xbfb8aa3b, v5
	v_exp_f32_e32 v12, v12
	v_exp_f32_e32 v13, v13
	v_mul_f32_e32 v15, 0xbfb8aa3b, v7
	v_exp_f32_e32 v14, v14
	v_exp_f32_e32 v15, v15
	v_add_f32_e32 v12, 1.0, v12
	v_add_f32_e32 v13, 1.0, v13
	v_rcp_f32_e32 v12, v12
	v_rcp_f32_e32 v13, v13
	v_add_f32_e32 v14, 1.0, v14
	v_add_f32_e32 v15, 1.0, v15
	v_rcp_f32_e32 v14, v14
	v_rcp_f32_e32 v15, v15
	v_cvt_pk_bf16_f32 v8, v8, v9
	v_cvt_pk_bf16_f32 v9, v10, v11
	v_mad_i64_i32 v[10:11], s[48:49], v20, s66, v[120:121]
	v_pk_mul_f32 v[4:5], v[4:5], v[12:13]
	v_lshl_add_u64 v[10:11], v[10:11], 0, s[56:57]
	v_pk_mul_f32 v[0:1], v[0:1], v[4:5]
	v_pk_mul_f32 v[4:5], v[6:7], v[14:15]
	v_lshl_add_u64 v[10:11], v[10:11], 0, s[10:11]
	v_pk_mul_f32 v[2:3], v[2:3], v[4:5]
	v_lshl_add_u64 v[10:11], v[10:11], 0, v[138:139]
	v_cvt_pk_bf16_f32 v0, v0, v1
	v_cvt_pk_bf16_f32 v1, v2, v3
	s_waitcnt vmcnt(7)
	buffer_store_dwordx4 v[166:169], v246, s[76:79], s5 offen nt
	buffer_store_dwordx4 v[170:173], v246, s[76:79], s5 offen offset:1024 nt
	buffer_store_dwordx4 v[174:177], v246, s[76:79], s5 offen offset:2048 nt
	buffer_store_dwordx4 v[178:181], v246, s[76:79], s5 offen offset:3072 nt
	buffer_store_dwordx4 v[182:185], v246, s[76:79], vcc_lo offen nt
	buffer_store_dwordx4 v[186:189], v246, s[76:79], vcc_lo offen offset:1024 nt
	s_add_u32 s5, s5, 0x18000
	s_cmp_ge_u32 s5, 0x78000
	s_cselect_b32 s5, 0x70000000, s5
	s_andn2_b64 vcc, exec, s[6:7]
	s_mov_b64 s[6:7], -1
	global_store_dwordx2 v[122:123], v[124:125], off
	global_store_dwordx2 v[106:107], v[104:105], off
	global_store_dwordx2 v[90:91], v[88:89], off
	global_store_dwordx2 v[74:75], v[72:73], off
	global_store_dwordx2 v[58:59], v[56:57], off
	global_store_dwordx2 v[42:43], v[40:41], off
	global_store_dwordx2 v[26:27], v[24:25], off
	global_store_dwordx2 v[10:11], v[8:9], off
	global_store_dwordx2 v[10:11], v[0:1], off offset:128
	s_cbranch_vccnz .LBB0_1654
	s_andn2_b64 vcc, exec, s[22:23]
	s_cbranch_vccnz .LBB0_1653
	s_barrier
	s_branch .LBB0_1653
